# pipelined RMSNorm loops: wave sum by DPP adds and permlane swaps instead of six waited ds_bpermute round trips
# speedup vs baseline: 1.0036x; 1.0036x over previous
.Lnorm_s7_a:
	v_and_b32_e32 v41, 0xffff0000, v22
	v_lshlrev_b32_e32 v40, 16, v22
	v_mul_f32_e32 v0, v41, v41
	v_lshlrev_b32_e32 v42, 16, v23
	v_fmac_f32_e32 v0, v40, v40
	v_and_b32_e32 v43, 0xffff0000, v23
	v_fmac_f32_e32 v0, v42, v42
	v_lshlrev_b32_e32 v44, 16, v24
	v_fmac_f32_e32 v0, v43, v43
	v_and_b32_e32 v45, 0xffff0000, v24
	v_fmac_f32_e32 v0, v44, v44
	v_lshlrev_b32_e32 v46, 16, v25
	v_fmac_f32_e32 v0, v45, v45
	v_and_b32_e32 v47, 0xffff0000, v25
	v_fmac_f32_e32 v0, v46, v46
	v_fmac_f32_e32 v0, v47, v47
	v_lshlrev_b32_e32 v22, 16, v28
	v_and_b32_e32 v23, 0xffff0000, v28
	v_fmac_f32_e32 v0, v22, v22
	v_lshlrev_b32_e32 v24, 16, v29
	v_fmac_f32_e32 v0, v23, v23
	v_and_b32_e32 v26, 0xffff0000, v30
	v_and_b32_e32 v25, 0xffff0000, v29
	v_fmac_f32_e32 v0, v24, v24
	v_lshlrev_b32_e32 v29, 16, v30
	v_mov_b32_e32 v28, v26
	v_fmac_f32_e32 v0, v25, v25
	v_pk_mul_f32 v[48:49], v[28:29], v[28:29]
	v_and_b32_e32 v27, s0, v31
	v_add_f32_e32 v0, v49, v0
	v_add_f32_e32 v19, v48, v0
	v_and_b32_e32 v0, 0xffff0000, v31
	v_lshlrev_b32_e32 v31, 16, v31
	v_mov_b32_e32 v30, v0
	v_pk_mul_f32 v[48:49], v[30:31], v[30:31]
	v_pk_mov_b32 v[26:27], v[28:29], v[26:27] op_sel:[1,0]
	v_add_f32_e32 v19, v49, v19
	v_add_f32_e32 v19, v48, v19
	v_pk_mov_b32 v[28:29], v[30:31], v[0:1] op_sel:[1,0]
	s_nop 1
	v_add_f32_dpp v19, v19, v19 quad_perm:[1,0,3,2] row_mask:0xf bank_mask:0xf
	s_nop 1
	v_add_f32_dpp v19, v19, v19 quad_perm:[2,3,0,1] row_mask:0xf bank_mask:0xf
	s_nop 1
	v_add_f32_dpp v19, v19, v19 row_half_mirror row_mask:0xf bank_mask:0xf
	s_nop 1
	v_add_f32_dpp v19, v19, v19 row_mirror row_mask:0xf bank_mask:0xf
	v_mov_b32_e32 v32, v19
	s_nop 1
	v_permlane16_swap_b32_e32 v19, v32
	v_add_f32_e32 v19, v19, v32
	v_mov_b32_e32 v32, v19
	s_nop 1
	v_permlane32_swap_b32_e32 v19, v32
	v_add_f32_e32 v19, v19, v32
	v_fmamk_f32 v19, v19, 0x3a800000, v194
	v_cmp_gt_f32_e32 vcc, s76, v19
	v_mul_f32_e32 v32, 0x4b800000, v19
	s_nop 0
	v_cndmask_b32_e32 v19, v19, v32, vcc
	v_rsq_f32_e32 v19, v19
	s_nop 0
	v_mul_f32_e32 v32, 0x45800000, v19
	v_cndmask_b32_e32 v32, v19, v32, vcc
	v_pk_mul_f32 v[40:41], v[40:41], v[32:33] op_sel_hi:[1,0]
	v_pk_mul_f32 v[42:43], v[42:43], v[32:33] op_sel_hi:[1,0]
	v_pk_mul_f32 v[44:45], v[44:45], v[32:33] op_sel_hi:[1,0]
	v_pk_mul_f32 v[42:43], v[8:9], v[42:43]
	v_pk_mul_f32 v[40:41], v[6:7], v[40:41]
	v_pk_mul_f32 v[44:45], v[2:3], v[44:45]
	v_cvt_pk_bf16_f32 v40, v40, v41
	v_cvt_pk_bf16_f32 v41, v42, v43
	v_cvt_pk_bf16_f32 v42, v44, v45
	v_add_co_u32_e32 v44, vcc, s12, v20
	v_pk_mul_f32 v[22:23], v[22:23], v[32:33] op_sel_hi:[1,0]
	v_pk_mul_f32 v[24:25], v[24:25], v[32:33] op_sel_hi:[1,0]
	v_pk_mul_f32 v[26:27], v[32:33], v[26:27] op_sel_hi:[0,1]
	v_addc_co_u32_e32 v45, vcc, -1, v21, vcc
	v_pk_mul_f32 v[24:25], v[16:17], v[24:25]
	v_pk_mul_f32 v[22:23], v[14:15], v[22:23]
	v_pk_mul_f32 v[26:27], v[10:11], v[26:27]
	v_cvt_pk_bf16_f32 v22, v22, v23
	v_cvt_pk_bf16_f32 v23, v24, v25
	v_cvt_pk_bf16_f32 v24, v26, v27
	v_add_co_u32_e32 v26, vcc, 0xea67e000, v20
	v_pk_mul_f32 v[46:47], v[46:47], v[32:33] op_sel_hi:[1,0]
	v_pk_mul_f32 v[28:29], v[32:33], v[28:29] op_sel_hi:[0,1]
	v_addc_co_u32_e32 v27, vcc, -1, v21, vcc
	v_pk_mul_f32 v[46:47], v[4:5], v[46:47]
	v_pk_mul_f32 v[28:29], v[12:13], v[28:29]
	v_cvt_pk_bf16_f32 v43, v46, v47
	v_cvt_pk_bf16_f32 v25, v28, v29
	global_store_dwordx4 v[44:45], v[40:43], off
	global_store_dwordx4 v[26:27], v[22:25], off offset:-3072
	s_add_i32 s17, s17, s32
	s_cmp_lt_i32 s17, 0x8000
	s_cselect_b32 s30, s36, 0
	s_cselect_b32 s31, s37, 0
	v_lshl_add_u64 v[20:21], v[20:21], 0, s[30:31]
	global_load_dwordx4 v[22:25], v[20:21], off
	global_load_dwordx4 v[28:31], v[20:21], off offset:1024
	s_cmp_ge_i32 s23, 0x8000
	s_cbranch_scc1 .Lnorm_s7_done
	s_waitcnt vmcnt(4)
	v_and_b32_e32 v41, 0xffff0000, v222
	v_lshlrev_b32_e32 v40, 16, v222
	v_mul_f32_e32 v0, v41, v41
	v_lshlrev_b32_e32 v42, 16, v223
	v_fmac_f32_e32 v0, v40, v40
	v_and_b32_e32 v43, 0xffff0000, v223
	v_fmac_f32_e32 v0, v42, v42
	v_lshlrev_b32_e32 v44, 16, v224
	v_fmac_f32_e32 v0, v43, v43
	v_and_b32_e32 v45, 0xffff0000, v224
	v_fmac_f32_e32 v0, v44, v44
	v_lshlrev_b32_e32 v46, 16, v225
	v_fmac_f32_e32 v0, v45, v45
	v_and_b32_e32 v47, 0xffff0000, v225
	v_fmac_f32_e32 v0, v46, v46
	v_fmac_f32_e32 v0, v47, v47
	v_lshlrev_b32_e32 v222, 16, v228
	v_and_b32_e32 v223, 0xffff0000, v228
	v_fmac_f32_e32 v0, v222, v222
	v_lshlrev_b32_e32 v224, 16, v229
	v_fmac_f32_e32 v0, v223, v223
	v_and_b32_e32 v226, 0xffff0000, v230
	v_and_b32_e32 v225, 0xffff0000, v229
	v_fmac_f32_e32 v0, v224, v224
	v_lshlrev_b32_e32 v229, 16, v230
	v_mov_b32_e32 v228, v226
	v_fmac_f32_e32 v0, v225, v225
	v_pk_mul_f32 v[48:49], v[228:229], v[228:229]
	v_and_b32_e32 v227, s0, v231
	v_add_f32_e32 v0, v49, v0
	v_add_f32_e32 v19, v48, v0
	v_and_b32_e32 v0, 0xffff0000, v231
	v_lshlrev_b32_e32 v231, 16, v231
	v_mov_b32_e32 v230, v0
	v_pk_mul_f32 v[48:49], v[230:231], v[230:231]
	v_pk_mov_b32 v[226:227], v[228:229], v[226:227] op_sel:[1,0]
	v_add_f32_e32 v19, v49, v19
	v_add_f32_e32 v19, v48, v19
	v_pk_mov_b32 v[228:229], v[230:231], v[0:1] op_sel:[1,0]
	s_nop 1
	v_add_f32_dpp v19, v19, v19 quad_perm:[1,0,3,2] row_mask:0xf bank_mask:0xf
	s_nop 1
	v_add_f32_dpp v19, v19, v19 quad_perm:[2,3,0,1] row_mask:0xf bank_mask:0xf
	s_nop 1
	v_add_f32_dpp v19, v19, v19 row_half_mirror row_mask:0xf bank_mask:0xf
	s_nop 1
	v_add_f32_dpp v19, v19, v19 row_mirror row_mask:0xf bank_mask:0xf
	v_mov_b32_e32 v32, v19
	s_nop 1
	v_permlane16_swap_b32_e32 v19, v32
	v_add_f32_e32 v19, v19, v32
	v_mov_b32_e32 v32, v19
	s_nop 1
	v_permlane32_swap_b32_e32 v19, v32
	v_add_f32_e32 v19, v19, v32
	v_fmamk_f32 v19, v19, 0x3a800000, v194
	v_cmp_gt_f32_e32 vcc, s76, v19
	v_mul_f32_e32 v32, 0x4b800000, v19
	s_nop 0
	v_cndmask_b32_e32 v19, v19, v32, vcc
	v_rsq_f32_e32 v19, v19
	s_nop 0
	v_mul_f32_e32 v32, 0x45800000, v19
	v_cndmask_b32_e32 v32, v19, v32, vcc
	v_pk_mul_f32 v[40:41], v[40:41], v[32:33] op_sel_hi:[1,0]
	v_pk_mul_f32 v[42:43], v[42:43], v[32:33] op_sel_hi:[1,0]
	v_pk_mul_f32 v[44:45], v[44:45], v[32:33] op_sel_hi:[1,0]
	v_pk_mul_f32 v[42:43], v[8:9], v[42:43]
	v_pk_mul_f32 v[40:41], v[6:7], v[40:41]
	v_pk_mul_f32 v[44:45], v[2:3], v[44:45]
	v_cvt_pk_bf16_f32 v40, v40, v41
	v_cvt_pk_bf16_f32 v41, v42, v43
	v_cvt_pk_bf16_f32 v42, v44, v45
	v_add_co_u32_e32 v44, vcc, s12, v204
	v_pk_mul_f32 v[222:223], v[222:223], v[32:33] op_sel_hi:[1,0]
	v_pk_mul_f32 v[224:225], v[224:225], v[32:33] op_sel_hi:[1,0]
	v_pk_mul_f32 v[226:227], v[32:33], v[226:227] op_sel_hi:[0,1]
	v_addc_co_u32_e32 v45, vcc, -1, v205, vcc
	v_pk_mul_f32 v[224:225], v[16:17], v[224:225]
	v_pk_mul_f32 v[222:223], v[14:15], v[222:223]
	v_pk_mul_f32 v[226:227], v[10:11], v[226:227]
	v_cvt_pk_bf16_f32 v222, v222, v223
	v_cvt_pk_bf16_f32 v223, v224, v225
	v_cvt_pk_bf16_f32 v224, v226, v227
	v_add_co_u32_e32 v226, vcc, 0xea67e000, v204
	v_pk_mul_f32 v[46:47], v[46:47], v[32:33] op_sel_hi:[1,0]
	v_pk_mul_f32 v[228:229], v[32:33], v[228:229] op_sel_hi:[0,1]
	v_addc_co_u32_e32 v227, vcc, -1, v205, vcc
	v_pk_mul_f32 v[46:47], v[4:5], v[46:47]
	v_pk_mul_f32 v[228:229], v[12:13], v[228:229]
	v_cvt_pk_bf16_f32 v43, v46, v47
	v_cvt_pk_bf16_f32 v225, v228, v229
	global_store_dwordx4 v[44:45], v[40:43], off
	global_store_dwordx4 v[226:227], v[222:225], off offset:-3072
	s_add_i32 s23, s23, s32
	s_cmp_lt_i32 s23, 0x8000
	s_cselect_b32 s30, s36, 0
	s_cselect_b32 s31, s37, 0
	v_lshl_add_u64 v[204:205], v[204:205], 0, s[30:31]
	global_load_dwordx4 v[222:225], v[204:205], off
	global_load_dwordx4 v[228:231], v[204:205], off offset:1024
	s_cmp_lt_i32 s17, 0x8000
	s_cbranch_scc1 .Lnorm_s7_loop

.Lnorm_s10_a:
	v_and_b32_e32 v41, 0xffff0000, v22
	v_lshlrev_b32_e32 v40, 16, v22
	v_mul_f32_e32 v0, v41, v41
	v_lshlrev_b32_e32 v42, 16, v23
	v_fmac_f32_e32 v0, v40, v40
	v_and_b32_e32 v43, 0xffff0000, v23
	v_fmac_f32_e32 v0, v42, v42
	v_lshlrev_b32_e32 v44, 16, v24
	v_fmac_f32_e32 v0, v43, v43
	v_and_b32_e32 v45, 0xffff0000, v24
	v_fmac_f32_e32 v0, v44, v44
	v_lshlrev_b32_e32 v46, 16, v25
	v_fmac_f32_e32 v0, v45, v45
	v_and_b32_e32 v47, 0xffff0000, v25
	v_fmac_f32_e32 v0, v46, v46
	v_fmac_f32_e32 v0, v47, v47
	v_lshlrev_b32_e32 v22, 16, v28
	v_and_b32_e32 v23, 0xffff0000, v28
	v_fmac_f32_e32 v0, v22, v22
	v_lshlrev_b32_e32 v24, 16, v29
	v_fmac_f32_e32 v0, v23, v23
	v_and_b32_e32 v26, 0xffff0000, v30
	v_and_b32_e32 v25, 0xffff0000, v29
	v_fmac_f32_e32 v0, v24, v24
	v_lshlrev_b32_e32 v29, 16, v30
	v_mov_b32_e32 v28, v26
	v_fmac_f32_e32 v0, v25, v25
	v_pk_mul_f32 v[48:49], v[28:29], v[28:29]
	v_and_b32_e32 v27, s0, v31
	v_add_f32_e32 v0, v49, v0
	v_add_f32_e32 v19, v48, v0
	v_and_b32_e32 v0, 0xffff0000, v31
	v_lshlrev_b32_e32 v31, 16, v31
	v_mov_b32_e32 v30, v0
	v_pk_mul_f32 v[48:49], v[30:31], v[30:31]
	v_pk_mov_b32 v[26:27], v[28:29], v[26:27] op_sel:[1,0]
	v_add_f32_e32 v19, v49, v19
	v_add_f32_e32 v19, v48, v19
	v_pk_mov_b32 v[28:29], v[30:31], v[0:1] op_sel:[1,0]
	s_nop 1
	v_add_f32_dpp v19, v19, v19 quad_perm:[1,0,3,2] row_mask:0xf bank_mask:0xf
	s_nop 1
	v_add_f32_dpp v19, v19, v19 quad_perm:[2,3,0,1] row_mask:0xf bank_mask:0xf
	s_nop 1
	v_add_f32_dpp v19, v19, v19 row_half_mirror row_mask:0xf bank_mask:0xf
	s_nop 1
	v_add_f32_dpp v19, v19, v19 row_mirror row_mask:0xf bank_mask:0xf
	v_mov_b32_e32 v32, v19
	s_nop 1
	v_permlane16_swap_b32_e32 v19, v32
	v_add_f32_e32 v19, v19, v32
	v_mov_b32_e32 v32, v19
	s_nop 1
	v_permlane32_swap_b32_e32 v19, v32
	v_add_f32_e32 v19, v19, v32
	v_fmamk_f32 v19, v19, 0x3a800000, v194
	v_cmp_gt_f32_e32 vcc, s76, v19
	v_mul_f32_e32 v32, 0x4b800000, v19
	s_nop 0
	v_cndmask_b32_e32 v19, v19, v32, vcc
	v_rsq_f32_e32 v19, v19
	s_nop 0
	v_mul_f32_e32 v32, 0x45800000, v19
	v_cndmask_b32_e32 v32, v19, v32, vcc
	v_pk_mul_f32 v[40:41], v[40:41], v[32:33] op_sel_hi:[1,0]
	v_pk_mul_f32 v[42:43], v[42:43], v[32:33] op_sel_hi:[1,0]
	v_pk_mul_f32 v[44:45], v[44:45], v[32:33] op_sel_hi:[1,0]
	v_pk_mul_f32 v[42:43], v[8:9], v[42:43]
	v_pk_mul_f32 v[40:41], v[6:7], v[40:41]
	v_pk_mul_f32 v[44:45], v[2:3], v[44:45]
	v_cvt_pk_bf16_f32 v40, v40, v41
	v_cvt_pk_bf16_f32 v41, v42, v43
	v_cvt_pk_bf16_f32 v42, v44, v45
	v_add_co_u32_e32 v44, vcc, s2, v20
	v_pk_mul_f32 v[22:23], v[22:23], v[32:33] op_sel_hi:[1,0]
	v_pk_mul_f32 v[24:25], v[24:25], v[32:33] op_sel_hi:[1,0]
	v_pk_mul_f32 v[26:27], v[32:33], v[26:27] op_sel_hi:[0,1]
	v_addc_co_u32_e32 v45, vcc, -1, v21, vcc
	v_pk_mul_f32 v[24:25], v[16:17], v[24:25]
	v_pk_mul_f32 v[22:23], v[14:15], v[22:23]
	v_pk_mul_f32 v[26:27], v[10:11], v[26:27]
	v_cvt_pk_bf16_f32 v22, v22, v23
	v_cvt_pk_bf16_f32 v23, v24, v25
	v_cvt_pk_bf16_f32 v24, v26, v27
	v_add_co_u32_e32 v26, vcc, 0xea67e000, v20
	v_pk_mul_f32 v[46:47], v[46:47], v[32:33] op_sel_hi:[1,0]
	v_pk_mul_f32 v[28:29], v[32:33], v[28:29] op_sel_hi:[0,1]
	v_addc_co_u32_e32 v27, vcc, -1, v21, vcc
	v_pk_mul_f32 v[46:47], v[4:5], v[46:47]
	v_pk_mul_f32 v[28:29], v[12:13], v[28:29]
	v_cvt_pk_bf16_f32 v43, v46, v47
	v_cvt_pk_bf16_f32 v25, v28, v29
	global_store_dwordx4 v[44:45], v[40:43], off
	global_store_dwordx4 v[26:27], v[22:25], off offset:-3072
	s_add_i32 s17, s17, s32
	s_cmp_lt_i32 s17, 0x8000
	s_cselect_b32 s18, s80, 0
	s_cselect_b32 s19, s81, 0
	v_lshl_add_u64 v[20:21], v[20:21], 0, s[18:19]
	global_load_dwordx4 v[22:25], v[20:21], off
	global_load_dwordx4 v[28:31], v[20:21], off offset:1024
	s_cmp_ge_i32 s23, 0x8000
	s_cbranch_scc1 .Lnorm_s10_done
	s_waitcnt vmcnt(4)
	v_and_b32_e32 v41, 0xffff0000, v222
	v_lshlrev_b32_e32 v40, 16, v222
	v_mul_f32_e32 v0, v41, v41
	v_lshlrev_b32_e32 v42, 16, v223
	v_fmac_f32_e32 v0, v40, v40
	v_and_b32_e32 v43, 0xffff0000, v223
	v_fmac_f32_e32 v0, v42, v42
	v_lshlrev_b32_e32 v44, 16, v224
	v_fmac_f32_e32 v0, v43, v43
	v_and_b32_e32 v45, 0xffff0000, v224
	v_fmac_f32_e32 v0, v44, v44
	v_lshlrev_b32_e32 v46, 16, v225
	v_fmac_f32_e32 v0, v45, v45
	v_and_b32_e32 v47, 0xffff0000, v225
	v_fmac_f32_e32 v0, v46, v46
	v_fmac_f32_e32 v0, v47, v47
	v_lshlrev_b32_e32 v222, 16, v228
	v_and_b32_e32 v223, 0xffff0000, v228
	v_fmac_f32_e32 v0, v222, v222
	v_lshlrev_b32_e32 v224, 16, v229
	v_fmac_f32_e32 v0, v223, v223
	v_and_b32_e32 v226, 0xffff0000, v230
	v_and_b32_e32 v225, 0xffff0000, v229
	v_fmac_f32_e32 v0, v224, v224
	v_lshlrev_b32_e32 v229, 16, v230
	v_mov_b32_e32 v228, v226
	v_fmac_f32_e32 v0, v225, v225
	v_pk_mul_f32 v[48:49], v[228:229], v[228:229]
	v_and_b32_e32 v227, s0, v231
	v_add_f32_e32 v0, v49, v0
	v_add_f32_e32 v19, v48, v0
	v_and_b32_e32 v0, 0xffff0000, v231
	v_lshlrev_b32_e32 v231, 16, v231
	v_mov_b32_e32 v230, v0
	v_pk_mul_f32 v[48:49], v[230:231], v[230:231]
	v_pk_mov_b32 v[226:227], v[228:229], v[226:227] op_sel:[1,0]
	v_add_f32_e32 v19, v49, v19
	v_add_f32_e32 v19, v48, v19
	v_pk_mov_b32 v[228:229], v[230:231], v[0:1] op_sel:[1,0]
	s_nop 1
	v_add_f32_dpp v19, v19, v19 quad_perm:[1,0,3,2] row_mask:0xf bank_mask:0xf
	s_nop 1
	v_add_f32_dpp v19, v19, v19 quad_perm:[2,3,0,1] row_mask:0xf bank_mask:0xf
	s_nop 1
	v_add_f32_dpp v19, v19, v19 row_half_mirror row_mask:0xf bank_mask:0xf
	s_nop 1
	v_add_f32_dpp v19, v19, v19 row_mirror row_mask:0xf bank_mask:0xf
	v_mov_b32_e32 v32, v19
	s_nop 1
	v_permlane16_swap_b32_e32 v19, v32
	v_add_f32_e32 v19, v19, v32
	v_mov_b32_e32 v32, v19
	s_nop 1
	v_permlane32_swap_b32_e32 v19, v32
	v_add_f32_e32 v19, v19, v32
	v_fmamk_f32 v19, v19, 0x3a800000, v194
	v_cmp_gt_f32_e32 vcc, s76, v19
	v_mul_f32_e32 v32, 0x4b800000, v19
	s_nop 0
	v_cndmask_b32_e32 v19, v19, v32, vcc
	v_rsq_f32_e32 v19, v19
	s_nop 0
	v_mul_f32_e32 v32, 0x45800000, v19
	v_cndmask_b32_e32 v32, v19, v32, vcc
	v_pk_mul_f32 v[40:41], v[40:41], v[32:33] op_sel_hi:[1,0]
	v_pk_mul_f32 v[42:43], v[42:43], v[32:33] op_sel_hi:[1,0]
	v_pk_mul_f32 v[44:45], v[44:45], v[32:33] op_sel_hi:[1,0]
	v_pk_mul_f32 v[42:43], v[8:9], v[42:43]
	v_pk_mul_f32 v[40:41], v[6:7], v[40:41]
	v_pk_mul_f32 v[44:45], v[2:3], v[44:45]
	v_cvt_pk_bf16_f32 v40, v40, v41
	v_cvt_pk_bf16_f32 v41, v42, v43
	v_cvt_pk_bf16_f32 v42, v44, v45
	v_add_co_u32_e32 v44, vcc, s2, v204
	v_pk_mul_f32 v[222:223], v[222:223], v[32:33] op_sel_hi:[1,0]
	v_pk_mul_f32 v[224:225], v[224:225], v[32:33] op_sel_hi:[1,0]
	v_pk_mul_f32 v[226:227], v[32:33], v[226:227] op_sel_hi:[0,1]
	v_addc_co_u32_e32 v45, vcc, -1, v205, vcc
	v_pk_mul_f32 v[224:225], v[16:17], v[224:225]
	v_pk_mul_f32 v[222:223], v[14:15], v[222:223]
	v_pk_mul_f32 v[226:227], v[10:11], v[226:227]
	v_cvt_pk_bf16_f32 v222, v222, v223
	v_cvt_pk_bf16_f32 v223, v224, v225
	v_cvt_pk_bf16_f32 v224, v226, v227
	v_add_co_u32_e32 v226, vcc, 0xea67e000, v204
	v_pk_mul_f32 v[46:47], v[46:47], v[32:33] op_sel_hi:[1,0]
	v_pk_mul_f32 v[228:229], v[32:33], v[228:229] op_sel_hi:[0,1]
	v_addc_co_u32_e32 v227, vcc, -1, v205, vcc
	v_pk_mul_f32 v[46:47], v[4:5], v[46:47]
	v_pk_mul_f32 v[228:229], v[12:13], v[228:229]
	v_cvt_pk_bf16_f32 v43, v46, v47
	v_cvt_pk_bf16_f32 v225, v228, v229
	global_store_dwordx4 v[44:45], v[40:43], off
	global_store_dwordx4 v[226:227], v[222:225], off offset:-3072
	s_add_i32 s23, s23, s32
	s_cmp_lt_i32 s23, 0x8000
	s_cselect_b32 s18, s80, 0
	s_cselect_b32 s19, s81, 0
	v_lshl_add_u64 v[204:205], v[204:205], 0, s[18:19]
	global_load_dwordx4 v[222:225], v[204:205], off
	global_load_dwordx4 v[228:231], v[204:205], off offset:1024
	s_cmp_lt_i32 s17, 0x8000
	s_cbranch_scc1 .Lnorm_s10_loop
